# attention fast loop: softmax row sums on the matrix core against a ones operand (the baseline's own method: bf16 P, f32 accumulate) instead of 16 v_pk_add_f32 per block-sub-tile; zero shift frees the
# baseline (speedup 1.0000x reference)
; #define LAS __attribute__((address_space(3)))
; #define AT_LOAD(K0, K1, V0, V1, T) do { const size_t e_ = (size_t)(128 * (T) + sr) * 64 + sc; \
;         K0 = *(const bf16x8*)(kcp + e_); V0 = *(const bf16x8*)(vcp + e_); K1 = *(const bf16x8*)(kcp + e_ + 64 * 64); V1 = *(const bf16x8*)(vcp + e_ + 64 * 64); } while (0)
; #define AT_STORE(K0, K1, V0, V1, BUF) do { *(LAS bf16x8*)(lds + AT_K + (BUF) * AT_KB + kst0) = K0; *(LAS bf16x8*)(lds + AT_K + (BUF) * AT_KB + kst1) = K1; \
;         *(LAS bf16x8*)(lds + AT_V + (BUF) * AT_VB + vst0) = V0; *(LAS bf16x8*)(lds + AT_V + (BUF) * AT_VB + vst1) = V1; } while (0)
; template <int VAR>
; __device__ __forceinline__ void attn_unit(const Args& a, int l, int b, int h, int qrow0  , bool ctxu, const bf16* Z, bf16* Y, LAS unsigned char* lds) {
;     ...
;     AT_LOAD(ka0, ka1, va0, va1, 0); AT_LOAD(kb0, kb1, vb0_, vb1_, 1); AT_STORE(ka0, ka1, va0, va1, 0);
;     const LAS unsigned char* Kb0 = lds + AT_K + comp * 64;
;     for (int t = 0; t < NT; t += 2) {
;         __syncthreads();
;         if (t + 2 < NT) AT_LOAD(ka0, ka1, va0, va1, t + 2);
;         attn_tile(Kb0, vb0, q0, q1, negm, m, o0, o1, lacc, t == 0, wsf, r32, hi);
.Lat_noprioF:
	s_waitcnt lgkmcnt(0)
	s_add_u32 m0, s51, 0x0
	s_nop 0
	global_load_lds_dwordx4 v158, s[36:37]
	s_add_u32 m0, s51, 0x2000
	s_nop 0
	global_load_lds_dwordx4 v159, s[36:37]
	s_add_u32 m0, s51, 0xc000
	s_nop 0
	global_load_lds_dwordx4 v160, s[48:49]
	s_add_u32 m0, s51, 0xe000
	s_nop 0
	global_load_lds_dwordx4 v161, s[48:49]
	s_add_u32 s36, s36, 0x4000
	s_addc_u32 s37, s37, 0
	s_add_u32 s48, s48, 0x4000
	s_addc_u32 s49, s49, 0
	s_add_u32 m0, s51, 0x4000
	s_nop 0
	global_load_lds_dwordx4 v158, s[36:37]
	s_add_u32 m0, s51, 0x6000
	s_nop 0
	global_load_lds_dwordx4 v159, s[36:37]
	s_add_u32 m0, s51, 0x10000
	s_nop 0
	global_load_lds_dwordx4 v160, s[48:49]
	s_add_u32 m0, s51, 0x12000
	s_nop 0
	global_load_lds_dwordx4 v161, s[48:49]
	s_add_u32 s36, s36, 0x4000
	s_addc_u32 s37, s37, 0
	s_add_u32 s48, s48, 0x4000
	s_addc_u32 s49, s49, 0
	s_waitcnt vmcnt(4)
	s_barrier
	s_add_u32 m0, s51, 0x8000
	s_nop 0
	global_load_lds_dwordx4 v158, s[36:37]
	s_add_u32 m0, s51, 0xa000
	s_nop 0
	global_load_lds_dwordx4 v159, s[36:37]
	s_add_u32 m0, s51, 0x14000
	s_nop 0
	global_load_lds_dwordx4 v160, s[48:49]
	s_add_u32 m0, s51, 0x16000
	s_nop 0
	global_load_lds_dwordx4 v161, s[48:49]
	s_add_u32 s36, s36, 0x4000
	s_addc_u32 s37, s37, 0
	s_add_u32 s48, s48, 0x4000
	s_addc_u32 s49, s49, 0
	ds_read_b128 v[48:51], v144 offset:0
	ds_read_b128 v[52:55], v145 offset:0
	ds_read_b128 v[56:59], v144 offset:4096
	ds_read_b128 v[60:63], v145 offset:4096
	v_mov_b32_e32 v132, 0x3f803f80
	v_mov_b32_e32 v133, 0x3f803f80
	v_mov_b32_e32 v134, 0x3f803f80
	v_mov_b32_e32 v135, 0x3f803f80
.Lat_floop:
	s_waitcnt lgkmcnt(0)
	v_mfma_f32_32x32x16_bf16 v[96:111], v[48:51], v[136:139], 0
	ds_read_b64_tr_b16 v[168:169], v146 offset:0
	ds_read_b64_tr_b16 v[170:171], v146 offset:1024
	ds_read_b64_tr_b16 v[172:173], v146 offset:512
	ds_read_b64_tr_b16 v[174:175], v146 offset:1536
	v_mfma_f32_32x32x16_bf16 v[96:111], v[52:55], v[140:143], v[96:111]
	ds_read_b64_tr_b16 v[176:177], v146 offset:2048
	ds_read_b64_tr_b16 v[178:179], v146 offset:3072
	ds_read_b64_tr_b16 v[180:181], v146 offset:2560
	ds_read_b64_tr_b16 v[182:183], v146 offset:3584
	v_mfma_f32_32x32x16_bf16 v[112:127], v[56:59], v[136:139], 0
	ds_read_b64_tr_b16 v[184:185], v146 offset:4096
	ds_read_b64_tr_b16 v[186:187], v146 offset:5120
	ds_read_b64_tr_b16 v[188:189], v146 offset:4608
	ds_read_b64_tr_b16 v[190:191], v146 offset:5632
	v_mfma_f32_32x32x16_bf16 v[112:127], v[60:63], v[140:143], v[112:127]
	ds_read_b64_tr_b16 v[192:193], v146 offset:6144
	ds_read_b64_tr_b16 v[194:195], v146 offset:7168
	ds_read_b64_tr_b16 v[196:197], v146 offset:6656
	ds_read_b64_tr_b16 v[198:199], v146 offset:7680
	v_exp_f32_e32 v96, v96
	v_exp_f32_e32 v97, v97
	v_exp_f32_e32 v98, v98
	v_exp_f32_e32 v99, v99
	v_exp_f32_e32 v100, v100
	v_exp_f32_e32 v101, v101
	v_exp_f32_e32 v102, v102
	v_exp_f32_e32 v103, v103
	v_cvt_pk_bf16_f32 v162, v96, v97
	v_cvt_pk_bf16_f32 v163, v98, v99
	v_cvt_pk_bf16_f32 v164, v100, v101
	v_cvt_pk_bf16_f32 v165, v102, v103
	s_waitcnt lgkmcnt(12)
	s_nop 0
	v_mfma_f32_32x32x16_bf16 v[0:15], v[162:165], v[168:171], v[0:15]
	v_exp_f32_e32 v104, v104
	v_exp_f32_e32 v105, v105
	v_mfma_f32_32x32x16_bf16 v[32:47], v[162:165], v[132:135], v[32:47]
	v_exp_f32_e32 v106, v106
	v_exp_f32_e32 v107, v107
	v_mfma_f32_32x32x16_bf16 v[16:31], v[162:165], v[172:175], v[16:31]
	v_exp_f32_e32 v108, v108
	v_exp_f32_e32 v109, v109
	v_exp_f32_e32 v110, v110
	v_exp_f32_e32 v111, v111
	v_cvt_pk_bf16_f32 v162, v104, v105
	v_cvt_pk_bf16_f32 v163, v106, v107
	v_cvt_pk_bf16_f32 v164, v108, v109
	v_cvt_pk_bf16_f32 v165, v110, v111
	s_waitcnt lgkmcnt(8)
	s_nop 0
	v_mfma_f32_32x32x16_bf16 v[0:15], v[162:165], v[176:179], v[0:15]
	v_exp_f32_e32 v112, v112
	v_exp_f32_e32 v113, v113
	v_mfma_f32_32x32x16_bf16 v[32:47], v[162:165], v[132:135], v[32:47]
	v_exp_f32_e32 v114, v114
	v_exp_f32_e32 v115, v115
	v_mfma_f32_32x32x16_bf16 v[16:31], v[162:165], v[180:183], v[16:31]
	v_mfma_f32_32x32x16_bf16 v[96:111], v[48:51], v[150:153], 0
	v_exp_f32_e32 v116, v116
	v_exp_f32_e32 v117, v117
	v_exp_f32_e32 v118, v118
	v_exp_f32_e32 v119, v119
	v_mfma_f32_32x32x16_bf16 v[96:111], v[52:55], v[154:157], v[96:111]
	v_cvt_pk_bf16_f32 v162, v112, v113
	v_cvt_pk_bf16_f32 v163, v114, v115
	v_cvt_pk_bf16_f32 v164, v116, v117
	v_cvt_pk_bf16_f32 v165, v118, v119
	s_waitcnt lgkmcnt(4)
	s_nop 0
	v_mfma_f32_32x32x16_bf16 v[0:15], v[162:165], v[184:187], v[0:15]
	v_exp_f32_e32 v120, v120
	v_exp_f32_e32 v121, v121
	v_mfma_f32_32x32x16_bf16 v[32:47], v[162:165], v[132:135], v[32:47]
	v_exp_f32_e32 v122, v122
	v_exp_f32_e32 v123, v123
	v_mfma_f32_32x32x16_bf16 v[16:31], v[162:165], v[188:191], v[16:31]
	v_exp_f32_e32 v124, v124
	v_exp_f32_e32 v125, v125
	v_exp_f32_e32 v126, v126
	v_exp_f32_e32 v127, v127
	v_cvt_pk_bf16_f32 v162, v120, v121
	v_cvt_pk_bf16_f32 v163, v122, v123
	v_cvt_pk_bf16_f32 v164, v124, v125
	v_cvt_pk_bf16_f32 v165, v126, v127
	v_mfma_f32_32x32x16_bf16 v[112:127], v[56:59], v[150:153], 0
	v_mfma_f32_32x32x16_bf16 v[112:127], v[60:63], v[154:157], v[112:127]
	s_waitcnt lgkmcnt(0)
	s_nop 0
	v_mfma_f32_32x32x16_bf16 v[0:15], v[162:165], v[192:195], v[0:15]
	v_exp_f32_e32 v96, v96
	v_exp_f32_e32 v97, v97
	v_mfma_f32_32x32x16_bf16 v[32:47], v[162:165], v[132:135], v[32:47]
	v_exp_f32_e32 v98, v98
	v_exp_f32_e32 v99, v99
	v_mfma_f32_32x32x16_bf16 v[16:31], v[162:165], v[196:199], v[16:31]
	ds_read_b128 v[48:51], v144 offset:8192
	ds_read_b128 v[52:55], v145 offset:8192
	ds_read_b128 v[56:59], v144 offset:12288
	ds_read_b128 v[60:63], v145 offset:12288
	v_exp_f32_e32 v100, v100
	v_exp_f32_e32 v101, v101
	v_exp_f32_e32 v102, v102
	v_exp_f32_e32 v103, v103
	v_cvt_pk_bf16_f32 v162, v96, v97
	v_cvt_pk_bf16_f32 v163, v98, v99
	v_cvt_pk_bf16_f32 v164, v100, v101
	v_cvt_pk_bf16_f32 v165, v102, v103
	s_nop 1
	v_mfma_f32_32x32x16_bf16 v[80:95], v[162:165], v[168:171], v[80:95]
	v_exp_f32_e32 v104, v104
	v_exp_f32_e32 v105, v105
	v_mfma_f32_32x32x16_bf16 v[64:79], v[162:165], v[132:135], v[64:79]
	v_exp_f32_e32 v106, v106
	v_exp_f32_e32 v107, v107
	v_mfma_f32_32x32x16_bf16 v[200:215], v[162:165], v[172:175], v[200:215]
	v_exp_f32_e32 v108, v108
	v_exp_f32_e32 v109, v109
	v_exp_f32_e32 v110, v110
	v_exp_f32_e32 v111, v111
	v_cvt_pk_bf16_f32 v162, v104, v105
	v_cvt_pk_bf16_f32 v163, v106, v107
	v_cvt_pk_bf16_f32 v164, v108, v109
	v_cvt_pk_bf16_f32 v165, v110, v111
	s_nop 1
	v_mfma_f32_32x32x16_bf16 v[80:95], v[162:165], v[176:179], v[80:95]
	v_exp_f32_e32 v112, v112
	v_exp_f32_e32 v113, v113
	v_mfma_f32_32x32x16_bf16 v[64:79], v[162:165], v[132:135], v[64:79]
	v_exp_f32_e32 v114, v114
	v_exp_f32_e32 v115, v115
	v_mfma_f32_32x32x16_bf16 v[200:215], v[162:165], v[180:183], v[200:215]
	v_exp_f32_e32 v116, v116
	v_exp_f32_e32 v117, v117
	v_exp_f32_e32 v118, v118
	v_exp_f32_e32 v119, v119
	v_cvt_pk_bf16_f32 v162, v112, v113
	v_cvt_pk_bf16_f32 v163, v114, v115
	v_cvt_pk_bf16_f32 v164, v116, v117
	v_cvt_pk_bf16_f32 v165, v118, v119
	s_nop 1
	v_mfma_f32_32x32x16_bf16 v[80:95], v[162:165], v[184:187], v[80:95]
	v_exp_f32_e32 v120, v120
	v_exp_f32_e32 v121, v121
	v_mfma_f32_32x32x16_bf16 v[64:79], v[162:165], v[132:135], v[64:79]
	v_exp_f32_e32 v122, v122
	v_exp_f32_e32 v123, v123
	v_mfma_f32_32x32x16_bf16 v[200:215], v[162:165], v[188:191], v[200:215]
	v_exp_f32_e32 v124, v124
	v_exp_f32_e32 v125, v125
	v_exp_f32_e32 v126, v126
	v_exp_f32_e32 v127, v127
	v_cvt_pk_bf16_f32 v162, v120, v121
	v_cvt_pk_bf16_f32 v163, v122, v123
	v_cvt_pk_bf16_f32 v164, v124, v125
	v_cvt_pk_bf16_f32 v165, v126, v127
	s_nop 1
	v_mfma_f32_32x32x16_bf16 v[80:95], v[162:165], v[192:195], v[80:95]
	v_mfma_f32_32x32x16_bf16 v[64:79], v[162:165], v[132:135], v[64:79]
	v_mfma_f32_32x32x16_bf16 v[200:215], v[162:165], v[196:199], v[200:215]
	s_waitcnt lgkmcnt(0)
	v_mfma_f32_32x32x16_bf16 v[96:111], v[48:51], v[136:139], 0
	ds_read_b64_tr_b16 v[168:169], v146 offset:8192
	ds_read_b64_tr_b16 v[170:171], v146 offset:9216
	ds_read_b64_tr_b16 v[172:173], v146 offset:8704
	ds_read_b64_tr_b16 v[174:175], v146 offset:9728
	v_mfma_f32_32x32x16_bf16 v[96:111], v[52:55], v[140:143], v[96:111]
	ds_read_b64_tr_b16 v[176:177], v146 offset:10240
	ds_read_b64_tr_b16 v[178:179], v146 offset:11264
	ds_read_b64_tr_b16 v[180:181], v146 offset:10752
	ds_read_b64_tr_b16 v[182:183], v146 offset:11776
	v_mfma_f32_32x32x16_bf16 v[112:127], v[56:59], v[136:139], 0
	ds_read_b64_tr_b16 v[184:185], v146 offset:12288
	ds_read_b64_tr_b16 v[186:187], v146 offset:13312
	ds_read_b64_tr_b16 v[188:189], v146 offset:12800
	ds_read_b64_tr_b16 v[190:191], v146 offset:13824
	v_mfma_f32_32x32x16_bf16 v[112:127], v[60:63], v[140:143], v[112:127]
	ds_read_b64_tr_b16 v[192:193], v146 offset:14336
	ds_read_b64_tr_b16 v[194:195], v146 offset:15360
	ds_read_b64_tr_b16 v[196:197], v146 offset:14848
	ds_read_b64_tr_b16 v[198:199], v146 offset:15872
	v_exp_f32_e32 v96, v96
	v_exp_f32_e32 v97, v97
	v_exp_f32_e32 v98, v98
	v_exp_f32_e32 v99, v99
	v_exp_f32_e32 v100, v100
	v_exp_f32_e32 v101, v101
	v_exp_f32_e32 v102, v102
	v_exp_f32_e32 v103, v103
	v_cvt_pk_bf16_f32 v162, v96, v97
	v_cvt_pk_bf16_f32 v163, v98, v99
	v_cvt_pk_bf16_f32 v164, v100, v101
	v_cvt_pk_bf16_f32 v165, v102, v103
	s_waitcnt lgkmcnt(12)
	s_nop 0
	v_mfma_f32_32x32x16_bf16 v[0:15], v[162:165], v[168:171], v[0:15]
	v_exp_f32_e32 v104, v104
	v_exp_f32_e32 v105, v105
	v_mfma_f32_32x32x16_bf16 v[32:47], v[162:165], v[132:135], v[32:47]
	v_exp_f32_e32 v106, v106
	v_exp_f32_e32 v107, v107
	v_mfma_f32_32x32x16_bf16 v[16:31], v[162:165], v[172:175], v[16:31]
	v_exp_f32_e32 v108, v108
	v_exp_f32_e32 v109, v109
	v_exp_f32_e32 v110, v110
	v_exp_f32_e32 v111, v111
	v_cvt_pk_bf16_f32 v162, v104, v105
	v_cvt_pk_bf16_f32 v163, v106, v107
	v_cvt_pk_bf16_f32 v164, v108, v109
	v_cvt_pk_bf16_f32 v165, v110, v111
	s_waitcnt lgkmcnt(8)
	s_nop 0
	v_mfma_f32_32x32x16_bf16 v[0:15], v[162:165], v[176:179], v[0:15]
	v_exp_f32_e32 v112, v112
	v_exp_f32_e32 v113, v113
	v_mfma_f32_32x32x16_bf16 v[32:47], v[162:165], v[132:135], v[32:47]
	v_exp_f32_e32 v114, v114
	v_exp_f32_e32 v115, v115
	v_mfma_f32_32x32x16_bf16 v[16:31], v[162:165], v[180:183], v[16:31]
	v_mfma_f32_32x32x16_bf16 v[96:111], v[48:51], v[150:153], 0
	v_exp_f32_e32 v116, v116
	v_exp_f32_e32 v117, v117
	v_exp_f32_e32 v118, v118
	v_exp_f32_e32 v119, v119
	v_mfma_f32_32x32x16_bf16 v[96:111], v[52:55], v[154:157], v[96:111]
	v_cvt_pk_bf16_f32 v162, v112, v113
	v_cvt_pk_bf16_f32 v163, v114, v115
	v_cvt_pk_bf16_f32 v164, v116, v117
	v_cvt_pk_bf16_f32 v165, v118, v119
	s_waitcnt lgkmcnt(4)
; #define LAS __attribute__((address_space(3)))
; #define AT_LOAD(K0, K1, V0, V1, T) do { const size_t e_ = (size_t)(128 * (T) + sr) * 64 + sc; \
;         K0 = *(const bf16x8*)(kcp + e_); V0 = *(const bf16x8*)(vcp + e_); K1 = *(const bf16x8*)(kcp + e_ + 64 * 64); V1 = *(const bf16x8*)(vcp + e_ + 64 * 64); } while (0)
; #define AT_STORE(K0, K1, V0, V1, BUF) do { *(LAS bf16x8*)(lds + AT_K + (BUF) * AT_KB + kst0) = K0; *(LAS bf16x8*)(lds + AT_K + (BUF) * AT_KB + kst1) = K1; \
;         *(LAS bf16x8*)(lds + AT_V + (BUF) * AT_VB + vst0) = V0; *(LAS bf16x8*)(lds + AT_V + (BUF) * AT_VB + vst1) = V1; } while (0)
; template <int VAR>
; __device__ __forceinline__ void attn_unit(const Args& a, int l, int b, int h, int qrow0  , bool ctxu, const bf16* Z, bf16* Y, LAS unsigned char* lds) {
;     ...
;     AT_LOAD(ka0, ka1, va0, va1, 0); AT_LOAD(kb0, kb1, vb0_, vb1_, 1); AT_STORE(ka0, ka1, va0, va1, 0);
;     const LAS unsigned char* Kb0 = lds + AT_K + comp * 64;
;     for (int t = 0; t < NT; t += 2) {
;         __syncthreads();
;         if (t + 2 < NT) AT_LOAD(ka0, ka1, va0, va1, t + 2);
;         attn_tile(Kb0, vb0, q0, q1, negm, m, o0, o1, lacc, t == 0, wsf, r32, hi);
;         AT_STORE(kb0, kb1, vb0_, vb1_, 1);
;         __syncthreads();
;         if (t + 3 < NT) AT_LOAD(kb0, kb1, vb0_, vb1_, t + 3);
;         attn_tile(Kb0 + AT_KB, vb0 + AT_VB, q0, q1, negm, m, o0, o1, lacc, false, wsf, r32, hi);
;         if (t + 2 < NT) AT_STORE(ka0, ka1, va0, va1, 0);
	s_nop 0
	v_mfma_f32_32x32x16_bf16 v[0:15], v[162:165], v[184:187], v[0:15]
	v_exp_f32_e32 v120, v120
	v_exp_f32_e32 v121, v121
	v_mfma_f32_32x32x16_bf16 v[32:47], v[162:165], v[132:135], v[32:47]
	v_exp_f32_e32 v122, v122
	v_exp_f32_e32 v123, v123
	v_mfma_f32_32x32x16_bf16 v[16:31], v[162:165], v[188:191], v[16:31]
	v_exp_f32_e32 v124, v124
	v_exp_f32_e32 v125, v125
	v_exp_f32_e32 v126, v126
	v_exp_f32_e32 v127, v127
	v_cvt_pk_bf16_f32 v162, v120, v121
	v_cvt_pk_bf16_f32 v163, v122, v123
	v_cvt_pk_bf16_f32 v164, v124, v125
	v_cvt_pk_bf16_f32 v165, v126, v127
	v_mfma_f32_32x32x16_bf16 v[112:127], v[56:59], v[150:153], 0
	v_mfma_f32_32x32x16_bf16 v[112:127], v[60:63], v[154:157], v[112:127]
	s_waitcnt lgkmcnt(0)
	s_nop 0
	v_mfma_f32_32x32x16_bf16 v[0:15], v[162:165], v[192:195], v[0:15]
	v_exp_f32_e32 v96, v96
	v_exp_f32_e32 v97, v97
	v_mfma_f32_32x32x16_bf16 v[32:47], v[162:165], v[132:135], v[32:47]
	v_exp_f32_e32 v98, v98
	v_exp_f32_e32 v99, v99
	v_mfma_f32_32x32x16_bf16 v[16:31], v[162:165], v[196:199], v[16:31]
	v_exp_f32_e32 v100, v100
	v_exp_f32_e32 v101, v101
	v_exp_f32_e32 v102, v102
	v_exp_f32_e32 v103, v103
	v_cvt_pk_bf16_f32 v162, v96, v97
	v_cvt_pk_bf16_f32 v163, v98, v99
	v_cvt_pk_bf16_f32 v164, v100, v101
	v_cvt_pk_bf16_f32 v165, v102, v103
	s_nop 1
	v_mfma_f32_32x32x16_bf16 v[80:95], v[162:165], v[168:171], v[80:95]
	v_exp_f32_e32 v104, v104
	v_exp_f32_e32 v105, v105
	v_mfma_f32_32x32x16_bf16 v[64:79], v[162:165], v[132:135], v[64:79]
	v_exp_f32_e32 v106, v106
	v_exp_f32_e32 v107, v107
	v_mfma_f32_32x32x16_bf16 v[200:215], v[162:165], v[172:175], v[200:215]
	v_exp_f32_e32 v108, v108
	v_exp_f32_e32 v109, v109
	v_exp_f32_e32 v110, v110
	v_exp_f32_e32 v111, v111
	v_cvt_pk_bf16_f32 v162, v104, v105
	v_cvt_pk_bf16_f32 v163, v106, v107
	v_cvt_pk_bf16_f32 v164, v108, v109
	v_cvt_pk_bf16_f32 v165, v110, v111
	s_nop 1
	v_mfma_f32_32x32x16_bf16 v[80:95], v[162:165], v[176:179], v[80:95]
	v_exp_f32_e32 v112, v112
	v_exp_f32_e32 v113, v113
	v_mfma_f32_32x32x16_bf16 v[64:79], v[162:165], v[132:135], v[64:79]
	v_exp_f32_e32 v114, v114
	v_exp_f32_e32 v115, v115
	v_mfma_f32_32x32x16_bf16 v[200:215], v[162:165], v[180:183], v[200:215]
	v_exp_f32_e32 v116, v116
	v_exp_f32_e32 v117, v117
	v_exp_f32_e32 v118, v118
	v_exp_f32_e32 v119, v119
	v_cvt_pk_bf16_f32 v162, v112, v113
	v_cvt_pk_bf16_f32 v163, v114, v115
	v_cvt_pk_bf16_f32 v164, v116, v117
	v_cvt_pk_bf16_f32 v165, v118, v119
	s_nop 1
	v_mfma_f32_32x32x16_bf16 v[80:95], v[162:165], v[184:187], v[80:95]
	v_exp_f32_e32 v120, v120
	v_exp_f32_e32 v121, v121
	v_mfma_f32_32x32x16_bf16 v[64:79], v[162:165], v[132:135], v[64:79]
	v_exp_f32_e32 v122, v122
	v_exp_f32_e32 v123, v123
	v_mfma_f32_32x32x16_bf16 v[200:215], v[162:165], v[188:191], v[200:215]
	v_exp_f32_e32 v124, v124
	v_exp_f32_e32 v125, v125
	v_exp_f32_e32 v126, v126
	v_exp_f32_e32 v127, v127
	v_cvt_pk_bf16_f32 v162, v120, v121
	v_cvt_pk_bf16_f32 v163, v122, v123
	v_cvt_pk_bf16_f32 v164, v124, v125
	v_cvt_pk_bf16_f32 v165, v126, v127
	s_waitcnt vmcnt(4)
	s_waitcnt lgkmcnt(0)
	s_barrier
	s_cmp_eq_u32 s33, 21
	s_cbranch_scc1 .Lat_ndF1
	s_add_u32 m0, s51, 0x0
	s_nop 0
	global_load_lds_dwordx4 v158, s[36:37]
	s_add_u32 m0, s51, 0x2000
	s_nop 0
	global_load_lds_dwordx4 v159, s[36:37]
	s_add_u32 m0, s51, 0xc000
	s_nop 0
	global_load_lds_dwordx4 v160, s[48:49]
	s_add_u32 m0, s51, 0xe000
	s_nop 0
	global_load_lds_dwordx4 v161, s[48:49]
	s_add_u32 s36, s36, 0x4000
	s_addc_u32 s37, s37, 0
	s_add_u32 s48, s48, 0x4000
	s_addc_u32 s49, s49, 0
.Lat_ndF1:
	ds_read_b128 v[48:51], v144 offset:16384
	ds_read_b128 v[52:55], v145 offset:16384
	ds_read_b128 v[56:59], v144 offset:20480
	ds_read_b128 v[60:63], v145 offset:20480
	s_nop 1
	v_mfma_f32_32x32x16_bf16 v[80:95], v[162:165], v[192:195], v[80:95]
	v_mfma_f32_32x32x16_bf16 v[64:79], v[162:165], v[132:135], v[64:79]
	v_mfma_f32_32x32x16_bf16 v[200:215], v[162:165], v[196:199], v[200:215]
	s_waitcnt lgkmcnt(0)
	v_mfma_f32_32x32x16_bf16 v[96:111], v[48:51], v[136:139], 0
	ds_read_b64_tr_b16 v[168:169], v146 offset:16384
	ds_read_b64_tr_b16 v[170:171], v146 offset:17408
	ds_read_b64_tr_b16 v[172:173], v146 offset:16896
	ds_read_b64_tr_b16 v[174:175], v146 offset:17920
	v_mfma_f32_32x32x16_bf16 v[96:111], v[52:55], v[140:143], v[96:111]
	ds_read_b64_tr_b16 v[176:177], v146 offset:18432
	ds_read_b64_tr_b16 v[178:179], v146 offset:19456
	ds_read_b64_tr_b16 v[180:181], v146 offset:18944
	ds_read_b64_tr_b16 v[182:183], v146 offset:19968
	v_mfma_f32_32x32x16_bf16 v[112:127], v[56:59], v[136:139], 0
	ds_read_b64_tr_b16 v[184:185], v146 offset:20480
	ds_read_b64_tr_b16 v[186:187], v146 offset:21504
	ds_read_b64_tr_b16 v[188:189], v146 offset:20992
	ds_read_b64_tr_b16 v[190:191], v146 offset:22016
	v_mfma_f32_32x32x16_bf16 v[112:127], v[60:63], v[140:143], v[112:127]
	ds_read_b64_tr_b16 v[192:193], v146 offset:22528
	ds_read_b64_tr_b16 v[194:195], v146 offset:23552
	ds_read_b64_tr_b16 v[196:197], v146 offset:23040
	ds_read_b64_tr_b16 v[198:199], v146 offset:24064
	v_exp_f32_e32 v96, v96
	v_exp_f32_e32 v97, v97
	v_exp_f32_e32 v98, v98
	v_exp_f32_e32 v99, v99
	v_exp_f32_e32 v100, v100
	v_exp_f32_e32 v101, v101
	v_exp_f32_e32 v102, v102
	v_exp_f32_e32 v103, v103
	v_cvt_pk_bf16_f32 v162, v96, v97
	v_cvt_pk_bf16_f32 v163, v98, v99
	v_cvt_pk_bf16_f32 v164, v100, v101
	v_cvt_pk_bf16_f32 v165, v102, v103
	s_waitcnt lgkmcnt(12)
	s_nop 0
	v_mfma_f32_32x32x16_bf16 v[0:15], v[162:165], v[168:171], v[0:15]
	v_exp_f32_e32 v104, v104
	v_exp_f32_e32 v105, v105
	v_mfma_f32_32x32x16_bf16 v[32:47], v[162:165], v[132:135], v[32:47]
	v_exp_f32_e32 v106, v106
	v_exp_f32_e32 v107, v107
	v_mfma_f32_32x32x16_bf16 v[16:31], v[162:165], v[172:175], v[16:31]
	v_exp_f32_e32 v108, v108
	v_exp_f32_e32 v109, v109
	v_exp_f32_e32 v110, v110
	v_exp_f32_e32 v111, v111
	v_cvt_pk_bf16_f32 v162, v104, v105
	v_cvt_pk_bf16_f32 v163, v106, v107
	v_cvt_pk_bf16_f32 v164, v108, v109
	v_cvt_pk_bf16_f32 v165, v110, v111
	s_waitcnt lgkmcnt(8)
	s_nop 0
	v_mfma_f32_32x32x16_bf16 v[0:15], v[162:165], v[176:179], v[0:15]
	v_exp_f32_e32 v112, v112
	v_exp_f32_e32 v113, v113
	v_mfma_f32_32x32x16_bf16 v[32:47], v[162:165], v[132:135], v[32:47]
	v_exp_f32_e32 v114, v114
	v_exp_f32_e32 v115, v115
	v_mfma_f32_32x32x16_bf16 v[16:31], v[162:165], v[180:183], v[16:31]
	v_mfma_f32_32x32x16_bf16 v[96:111], v[48:51], v[150:153], 0
	v_exp_f32_e32 v116, v116
	v_exp_f32_e32 v117, v117
	v_exp_f32_e32 v118, v118
	v_exp_f32_e32 v119, v119
	v_mfma_f32_32x32x16_bf16 v[96:111], v[52:55], v[154:157], v[96:111]
	v_cvt_pk_bf16_f32 v162, v112, v113
	v_cvt_pk_bf16_f32 v163, v114, v115
	v_cvt_pk_bf16_f32 v164, v116, v117
	v_cvt_pk_bf16_f32 v165, v118, v119
	s_waitcnt lgkmcnt(4)
	s_nop 0
	v_mfma_f32_32x32x16_bf16 v[0:15], v[162:165], v[184:187], v[0:15]
	v_exp_f32_e32 v120, v120
	v_exp_f32_e32 v121, v121
	v_mfma_f32_32x32x16_bf16 v[32:47], v[162:165], v[132:135], v[32:47]
	v_exp_f32_e32 v122, v122
	v_exp_f32_e32 v123, v123
	v_mfma_f32_32x32x16_bf16 v[16:31], v[162:165], v[188:191], v[16:31]
	v_exp_f32_e32 v124, v124
	v_exp_f32_e32 v125, v125
	v_exp_f32_e32 v126, v126
	v_exp_f32_e32 v127, v127
	v_cvt_pk_bf16_f32 v162, v120, v121
	v_cvt_pk_bf16_f32 v163, v122, v123
	v_cvt_pk_bf16_f32 v164, v124, v125
	v_cvt_pk_bf16_f32 v165, v126, v127
	v_mfma_f32_32x32x16_bf16 v[112:127], v[56:59], v[150:153], 0
	v_mfma_f32_32x32x16_bf16 v[112:127], v[60:63], v[154:157], v[112:127]
	s_waitcnt lgkmcnt(0)
	s_nop 0
	v_mfma_f32_32x32x16_bf16 v[0:15], v[162:165], v[192:195], v[0:15]
	v_exp_f32_e32 v96, v96
	v_exp_f32_e32 v97, v97
	v_mfma_f32_32x32x16_bf16 v[32:47], v[162:165], v[132:135], v[32:47]
	v_exp_f32_e32 v98, v98
	v_exp_f32_e32 v99, v99
	v_mfma_f32_32x32x16_bf16 v[16:31], v[162:165], v[196:199], v[16:31]
	ds_read_b128 v[48:51], v144 offset:24576
	ds_read_b128 v[52:55], v145 offset:24576
	ds_read_b128 v[56:59], v144 offset:28672
	ds_read_b128 v[60:63], v145 offset:28672
	v_exp_f32_e32 v100, v100
	v_exp_f32_e32 v101, v101
	v_exp_f32_e32 v102, v102
	v_exp_f32_e32 v103, v103
	v_cvt_pk_bf16_f32 v162, v96, v97
	v_cvt_pk_bf16_f32 v163, v98, v99
	v_cvt_pk_bf16_f32 v164, v100, v101
	v_cvt_pk_bf16_f32 v165, v102, v103
	s_nop 1
	v_mfma_f32_32x32x16_bf16 v[80:95], v[162:165], v[168:171], v[80:95]
	v_exp_f32_e32 v104, v104
	v_exp_f32_e32 v105, v105
	v_mfma_f32_32x32x16_bf16 v[64:79], v[162:165], v[132:135], v[64:79]
	v_exp_f32_e32 v106, v106
	v_exp_f32_e32 v107, v107
	v_mfma_f32_32x32x16_bf16 v[200:215], v[162:165], v[172:175], v[200:215]
	v_exp_f32_e32 v108, v108
	v_exp_f32_e32 v109, v109
	v_exp_f32_e32 v110, v110
	v_exp_f32_e32 v111, v111
	v_cvt_pk_bf16_f32 v162, v104, v105
	v_cvt_pk_bf16_f32 v163, v106, v107
	v_cvt_pk_bf16_f32 v164, v108, v109
	v_cvt_pk_bf16_f32 v165, v110, v111
	s_nop 1
	v_mfma_f32_32x32x16_bf16 v[80:95], v[162:165], v[176:179], v[80:95]
	v_exp_f32_e32 v112, v112
	v_exp_f32_e32 v113, v113
	v_mfma_f32_32x32x16_bf16 v[64:79], v[162:165], v[132:135], v[64:79]
	v_exp_f32_e32 v114, v114
	v_exp_f32_e32 v115, v115
	v_mfma_f32_32x32x16_bf16 v[200:215], v[162:165], v[180:183], v[200:215]
	v_exp_f32_e32 v116, v116
	v_exp_f32_e32 v117, v117
	v_exp_f32_e32 v118, v118
	v_exp_f32_e32 v119, v119
	v_cvt_pk_bf16_f32 v162, v112, v113
	v_cvt_pk_bf16_f32 v163, v114, v115
	v_cvt_pk_bf16_f32 v164, v116, v117
	v_cvt_pk_bf16_f32 v165, v118, v119
	s_nop 1
	v_mfma_f32_32x32x16_bf16 v[80:95], v[162:165], v[184:187], v[80:95]
	v_exp_f32_e32 v120, v120
	v_exp_f32_e32 v121, v121
	v_mfma_f32_32x32x16_bf16 v[64:79], v[162:165], v[132:135], v[64:79]
	v_exp_f32_e32 v122, v122
	v_exp_f32_e32 v123, v123
	v_mfma_f32_32x32x16_bf16 v[200:215], v[162:165], v[188:191], v[200:215]
	v_exp_f32_e32 v124, v124
	v_exp_f32_e32 v125, v125
	v_exp_f32_e32 v126, v126
	v_exp_f32_e32 v127, v127
	v_cvt_pk_bf16_f32 v162, v120, v121
	v_cvt_pk_bf16_f32 v163, v122, v123
	v_cvt_pk_bf16_f32 v164, v124, v125
	v_cvt_pk_bf16_f32 v165, v126, v127
	s_nop 1
	v_mfma_f32_32x32x16_bf16 v[80:95], v[162:165], v[192:195], v[80:95]
	v_mfma_f32_32x32x16_bf16 v[64:79], v[162:165], v[132:135], v[64:79]
	v_mfma_f32_32x32x16_bf16 v[200:215], v[162:165], v[196:199], v[200:215]
	s_waitcnt lgkmcnt(0)
	v_mfma_f32_32x32x16_bf16 v[96:111], v[48:51], v[136:139], 0
	ds_read_b64_tr_b16 v[168:169], v146 offset:24576
	ds_read_b64_tr_b16 v[170:171], v146 offset:25600
	ds_read_b64_tr_b16 v[172:173], v146 offset:25088
	ds_read_b64_tr_b16 v[174:175], v146 offset:26112
	v_mfma_f32_32x32x16_bf16 v[96:111], v[52:55], v[140:143], v[96:111]
	ds_read_b64_tr_b16 v[176:177], v146 offset:26624
	ds_read_b64_tr_b16 v[178:179], v146 offset:27648
	ds_read_b64_tr_b16 v[180:181], v146 offset:27136
	ds_read_b64_tr_b16 v[182:183], v146 offset:28160
	v_mfma_f32_32x32x16_bf16 v[112:127], v[56:59], v[136:139], 0
	ds_read_b64_tr_b16 v[184:185], v146 offset:28672
	ds_read_b64_tr_b16 v[186:187], v146 offset:29696
	ds_read_b64_tr_b16 v[188:189], v146 offset:29184
	ds_read_b64_tr_b16 v[190:191], v146 offset:30208
	v_mfma_f32_32x32x16_bf16 v[112:127], v[60:63], v[140:143], v[112:127]
	ds_read_b64_tr_b16 v[192:193], v146 offset:30720
	ds_read_b64_tr_b16 v[194:195], v146 offset:31744
	ds_read_b64_tr_b16 v[196:197], v146 offset:31232
	ds_read_b64_tr_b16 v[198:199], v146 offset:32256
	v_exp_f32_e32 v96, v96
	v_exp_f32_e32 v97, v97
	v_exp_f32_e32 v98, v98
	v_exp_f32_e32 v99, v99
	v_exp_f32_e32 v100, v100
	v_exp_f32_e32 v101, v101
	v_exp_f32_e32 v102, v102
	v_exp_f32_e32 v103, v103
	v_cvt_pk_bf16_f32 v162, v96, v97
	v_cvt_pk_bf16_f32 v163, v98, v99
	v_cvt_pk_bf16_f32 v164, v100, v101
	v_cvt_pk_bf16_f32 v165, v102, v103
	s_waitcnt lgkmcnt(12)
	s_nop 0
	v_mfma_f32_32x32x16_bf16 v[0:15], v[162:165], v[168:171], v[0:15]
	v_exp_f32_e32 v104, v104
	v_exp_f32_e32 v105, v105
	v_mfma_f32_32x32x16_bf16 v[32:47], v[162:165], v[132:135], v[32:47]
	v_exp_f32_e32 v106, v106
	v_exp_f32_e32 v107, v107
	v_mfma_f32_32x32x16_bf16 v[16:31], v[162:165], v[172:175], v[16:31]
	v_exp_f32_e32 v108, v108
	v_exp_f32_e32 v109, v109
	v_exp_f32_e32 v110, v110
	v_exp_f32_e32 v111, v111
	v_cvt_pk_bf16_f32 v162, v104, v105
	v_cvt_pk_bf16_f32 v163, v106, v107
	v_cvt_pk_bf16_f32 v164, v108, v109
	v_cvt_pk_bf16_f32 v165, v110, v111
	s_waitcnt lgkmcnt(8)
	s_nop 0
	v_mfma_f32_32x32x16_bf16 v[0:15], v[162:165], v[176:179], v[0:15]
	v_exp_f32_e32 v112, v112
	v_exp_f32_e32 v113, v113
	v_mfma_f32_32x32x16_bf16 v[32:47], v[162:165], v[132:135], v[32:47]
	v_exp_f32_e32 v114, v114
	v_exp_f32_e32 v115, v115
	v_mfma_f32_32x32x16_bf16 v[16:31], v[162:165], v[180:183], v[16:31]
	v_mfma_f32_32x32x16_bf16 v[96:111], v[48:51], v[150:153], 0
	v_exp_f32_e32 v116, v116
	v_exp_f32_e32 v117, v117
	v_exp_f32_e32 v118, v118
	v_exp_f32_e32 v119, v119
	v_mfma_f32_32x32x16_bf16 v[96:111], v[52:55], v[154:157], v[96:111]
	v_cvt_pk_bf16_f32 v162, v112, v113
	v_cvt_pk_bf16_f32 v163, v114, v115
	v_cvt_pk_bf16_f32 v164, v116, v117
	v_cvt_pk_bf16_f32 v165, v118, v119
	s_waitcnt lgkmcnt(4)
	s_nop 0
	v_mfma_f32_32x32x16_bf16 v[0:15], v[162:165], v[184:187], v[0:15]
	v_exp_f32_e32 v120, v120
	v_exp_f32_e32 v121, v121
	v_mfma_f32_32x32x16_bf16 v[32:47], v[162:165], v[132:135], v[32:47]
	v_exp_f32_e32 v122, v122
	v_exp_f32_e32 v123, v123
	v_mfma_f32_32x32x16_bf16 v[16:31], v[162:165], v[188:191], v[16:31]
	v_exp_f32_e32 v124, v124
	v_exp_f32_e32 v125, v125
	v_exp_f32_e32 v126, v126
	v_exp_f32_e32 v127, v127
	v_cvt_pk_bf16_f32 v162, v120, v121
	v_cvt_pk_bf16_f32 v163, v122, v123
	v_cvt_pk_bf16_f32 v164, v124, v125
	v_cvt_pk_bf16_f32 v165, v126, v127
	v_mfma_f32_32x32x16_bf16 v[112:127], v[56:59], v[150:153], 0
	v_mfma_f32_32x32x16_bf16 v[112:127], v[60:63], v[154:157], v[112:127]
	s_waitcnt lgkmcnt(0)
	s_nop 0
	v_mfma_f32_32x32x16_bf16 v[0:15], v[162:165], v[192:195], v[0:15]
	v_exp_f32_e32 v96, v96
	v_exp_f32_e32 v97, v97
	v_mfma_f32_32x32x16_bf16 v[32:47], v[162:165], v[132:135], v[32:47]
	v_exp_f32_e32 v98, v98
	v_exp_f32_e32 v99, v99
	v_mfma_f32_32x32x16_bf16 v[16:31], v[162:165], v[196:199], v[16:31]
	v_exp_f32_e32 v100, v100
	v_exp_f32_e32 v101, v101
	v_exp_f32_e32 v102, v102
	v_exp_f32_e32 v103, v103
	v_cvt_pk_bf16_f32 v162, v96, v97
	v_cvt_pk_bf16_f32 v163, v98, v99
	v_cvt_pk_bf16_f32 v164, v100, v101
	v_cvt_pk_bf16_f32 v165, v102, v103
	s_nop 1
	v_mfma_f32_32x32x16_bf16 v[80:95], v[162:165], v[168:171], v[80:95]
	v_exp_f32_e32 v104, v104
	v_exp_f32_e32 v105, v105
	v_mfma_f32_32x32x16_bf16 v[64:79], v[162:165], v[132:135], v[64:79]
	v_exp_f32_e32 v106, v106
	v_exp_f32_e32 v107, v107
	v_mfma_f32_32x32x16_bf16 v[200:215], v[162:165], v[172:175], v[200:215]
	v_exp_f32_e32 v108, v108
	v_exp_f32_e32 v109, v109
	v_exp_f32_e32 v110, v110
	v_exp_f32_e32 v111, v111
	v_cvt_pk_bf16_f32 v162, v104, v105
	v_cvt_pk_bf16_f32 v163, v106, v107
	v_cvt_pk_bf16_f32 v164, v108, v109
	v_cvt_pk_bf16_f32 v165, v110, v111
	s_nop 1
	v_mfma_f32_32x32x16_bf16 v[80:95], v[162:165], v[176:179], v[80:95]
	v_exp_f32_e32 v112, v112
	v_exp_f32_e32 v113, v113
	v_mfma_f32_32x32x16_bf16 v[64:79], v[162:165], v[132:135], v[64:79]
	v_exp_f32_e32 v114, v114
	v_exp_f32_e32 v115, v115
	v_mfma_f32_32x32x16_bf16 v[200:215], v[162:165], v[180:183], v[200:215]
	v_exp_f32_e32 v116, v116
	v_exp_f32_e32 v117, v117
	v_exp_f32_e32 v118, v118
	v_exp_f32_e32 v119, v119
	v_cvt_pk_bf16_f32 v162, v112, v113
	v_cvt_pk_bf16_f32 v163, v114, v115
	v_cvt_pk_bf16_f32 v164, v116, v117
	v_cvt_pk_bf16_f32 v165, v118, v119
	s_nop 1
	v_mfma_f32_32x32x16_bf16 v[80:95], v[162:165], v[184:187], v[80:95]
	v_exp_f32_e32 v120, v120
	v_exp_f32_e32 v121, v121
	v_mfma_f32_32x32x16_bf16 v[64:79], v[162:165], v[132:135], v[64:79]
	v_exp_f32_e32 v122, v122
	v_exp_f32_e32 v123, v123
	v_mfma_f32_32x32x16_bf16 v[200:215], v[162:165], v[188:191], v[200:215]
	v_exp_f32_e32 v124, v124
	v_exp_f32_e32 v125, v125
	v_exp_f32_e32 v126, v126
	v_exp_f32_e32 v127, v127
	v_cvt_pk_bf16_f32 v162, v120, v121
	v_cvt_pk_bf16_f32 v163, v122, v123
	v_cvt_pk_bf16_f32 v164, v124, v125
	v_cvt_pk_bf16_f32 v165, v126, v127
	s_cmp_eq_u32 s33, 21
	s_cbranch_scc1 .Lat_w0F3
	s_waitcnt vmcnt(4)
	s_branch .Lat_wdF3

.Lat_ndF3:
	ds_read_b128 v[48:51], v144 offset:32768
	ds_read_b128 v[52:55], v145 offset:32768
	ds_read_b128 v[56:59], v144 offset:36864
	ds_read_b128 v[60:63], v145 offset:36864
	s_nop 1
	v_mfma_f32_32x32x16_bf16 v[80:95], v[162:165], v[192:195], v[80:95]
	v_mfma_f32_32x32x16_bf16 v[64:79], v[162:165], v[132:135], v[64:79]
	v_mfma_f32_32x32x16_bf16 v[200:215], v[162:165], v[196:199], v[200:215]
	s_waitcnt lgkmcnt(0)
	v_mfma_f32_32x32x16_bf16 v[96:111], v[48:51], v[136:139], 0
	ds_read_b64_tr_b16 v[168:169], v146 offset:32768
	ds_read_b64_tr_b16 v[170:171], v146 offset:33792
	ds_read_b64_tr_b16 v[172:173], v146 offset:33280
	ds_read_b64_tr_b16 v[174:175], v146 offset:34304
	v_mfma_f32_32x32x16_bf16 v[96:111], v[52:55], v[140:143], v[96:111]
	ds_read_b64_tr_b16 v[176:177], v146 offset:34816
	ds_read_b64_tr_b16 v[178:179], v146 offset:35840
	ds_read_b64_tr_b16 v[180:181], v146 offset:35328
	ds_read_b64_tr_b16 v[182:183], v146 offset:36352
	v_mfma_f32_32x32x16_bf16 v[112:127], v[56:59], v[136:139], 0
	ds_read_b64_tr_b16 v[184:185], v146 offset:36864
	ds_read_b64_tr_b16 v[186:187], v146 offset:37888
	ds_read_b64_tr_b16 v[188:189], v146 offset:37376
	ds_read_b64_tr_b16 v[190:191], v146 offset:38400
	v_mfma_f32_32x32x16_bf16 v[112:127], v[60:63], v[140:143], v[112:127]
	ds_read_b64_tr_b16 v[192:193], v146 offset:38912
	ds_read_b64_tr_b16 v[194:195], v146 offset:39936
	ds_read_b64_tr_b16 v[196:197], v146 offset:39424
	ds_read_b64_tr_b16 v[198:199], v146 offset:40448
	v_exp_f32_e32 v96, v96
	v_exp_f32_e32 v97, v97
	v_exp_f32_e32 v98, v98
	v_exp_f32_e32 v99, v99
	v_exp_f32_e32 v100, v100
	v_exp_f32_e32 v101, v101
	v_exp_f32_e32 v102, v102
	v_exp_f32_e32 v103, v103
	v_cvt_pk_bf16_f32 v162, v96, v97
	v_cvt_pk_bf16_f32 v163, v98, v99
	v_cvt_pk_bf16_f32 v164, v100, v101
	v_cvt_pk_bf16_f32 v165, v102, v103
	s_waitcnt lgkmcnt(12)
	s_nop 0
	v_mfma_f32_32x32x16_bf16 v[0:15], v[162:165], v[168:171], v[0:15]
	v_exp_f32_e32 v104, v104
	v_exp_f32_e32 v105, v105
	v_mfma_f32_32x32x16_bf16 v[32:47], v[162:165], v[132:135], v[32:47]
	v_exp_f32_e32 v106, v106
	v_exp_f32_e32 v107, v107
	v_mfma_f32_32x32x16_bf16 v[16:31], v[162:165], v[172:175], v[16:31]
	v_exp_f32_e32 v108, v108
	v_exp_f32_e32 v109, v109
	v_exp_f32_e32 v110, v110
	v_exp_f32_e32 v111, v111
	v_cvt_pk_bf16_f32 v162, v104, v105
	v_cvt_pk_bf16_f32 v163, v106, v107
	v_cvt_pk_bf16_f32 v164, v108, v109
	v_cvt_pk_bf16_f32 v165, v110, v111
	s_waitcnt lgkmcnt(8)
	s_nop 0
	v_mfma_f32_32x32x16_bf16 v[0:15], v[162:165], v[176:179], v[0:15]
	v_exp_f32_e32 v112, v112
	v_exp_f32_e32 v113, v113
	v_mfma_f32_32x32x16_bf16 v[32:47], v[162:165], v[132:135], v[32:47]
	v_exp_f32_e32 v114, v114
	v_exp_f32_e32 v115, v115
	v_mfma_f32_32x32x16_bf16 v[16:31], v[162:165], v[180:183], v[16:31]
	v_mfma_f32_32x32x16_bf16 v[96:111], v[48:51], v[150:153], 0
	v_exp_f32_e32 v116, v116
	v_exp_f32_e32 v117, v117
	v_exp_f32_e32 v118, v118
	v_exp_f32_e32 v119, v119
	v_mfma_f32_32x32x16_bf16 v[96:111], v[52:55], v[154:157], v[96:111]
	v_cvt_pk_bf16_f32 v162, v112, v113
	v_cvt_pk_bf16_f32 v163, v114, v115
	v_cvt_pk_bf16_f32 v164, v116, v117
	v_cvt_pk_bf16_f32 v165, v118, v119
	s_waitcnt lgkmcnt(4)
	s_nop 0
	v_mfma_f32_32x32x16_bf16 v[0:15], v[162:165], v[184:187], v[0:15]
	v_exp_f32_e32 v120, v120
	v_exp_f32_e32 v121, v121
	v_mfma_f32_32x32x16_bf16 v[32:47], v[162:165], v[132:135], v[32:47]
	v_exp_f32_e32 v122, v122
	v_exp_f32_e32 v123, v123
	v_mfma_f32_32x32x16_bf16 v[16:31], v[162:165], v[188:191], v[16:31]
	v_exp_f32_e32 v124, v124
	v_exp_f32_e32 v125, v125
	v_exp_f32_e32 v126, v126
	v_exp_f32_e32 v127, v127
	v_cvt_pk_bf16_f32 v162, v120, v121
	v_cvt_pk_bf16_f32 v163, v122, v123
	v_cvt_pk_bf16_f32 v164, v124, v125
	v_cvt_pk_bf16_f32 v165, v126, v127
	v_mfma_f32_32x32x16_bf16 v[112:127], v[56:59], v[150:153], 0
	v_mfma_f32_32x32x16_bf16 v[112:127], v[60:63], v[154:157], v[112:127]
	s_waitcnt lgkmcnt(0)
	s_nop 0
	v_mfma_f32_32x32x16_bf16 v[0:15], v[162:165], v[192:195], v[0:15]
	v_exp_f32_e32 v96, v96
	v_exp_f32_e32 v97, v97
	v_mfma_f32_32x32x16_bf16 v[32:47], v[162:165], v[132:135], v[32:47]
	v_exp_f32_e32 v98, v98
	v_exp_f32_e32 v99, v99
	v_mfma_f32_32x32x16_bf16 v[16:31], v[162:165], v[196:199], v[16:31]
	ds_read_b128 v[48:51], v144 offset:40960
	ds_read_b128 v[52:55], v145 offset:40960
	ds_read_b128 v[56:59], v144 offset:45056
	ds_read_b128 v[60:63], v145 offset:45056
	v_exp_f32_e32 v100, v100
	v_exp_f32_e32 v101, v101
	v_exp_f32_e32 v102, v102
	v_exp_f32_e32 v103, v103
	v_cvt_pk_bf16_f32 v162, v96, v97
	v_cvt_pk_bf16_f32 v163, v98, v99
	v_cvt_pk_bf16_f32 v164, v100, v101
	v_cvt_pk_bf16_f32 v165, v102, v103
	s_nop 1
	v_mfma_f32_32x32x16_bf16 v[80:95], v[162:165], v[168:171], v[80:95]
	v_exp_f32_e32 v104, v104
	v_exp_f32_e32 v105, v105
	v_mfma_f32_32x32x16_bf16 v[64:79], v[162:165], v[132:135], v[64:79]
	v_exp_f32_e32 v106, v106
	v_exp_f32_e32 v107, v107
	v_mfma_f32_32x32x16_bf16 v[200:215], v[162:165], v[172:175], v[200:215]
	v_exp_f32_e32 v108, v108
	v_exp_f32_e32 v109, v109
	v_exp_f32_e32 v110, v110
	v_exp_f32_e32 v111, v111
	v_cvt_pk_bf16_f32 v162, v104, v105
	v_cvt_pk_bf16_f32 v163, v106, v107
	v_cvt_pk_bf16_f32 v164, v108, v109
	v_cvt_pk_bf16_f32 v165, v110, v111
	s_nop 1
	v_mfma_f32_32x32x16_bf16 v[80:95], v[162:165], v[176:179], v[80:95]
	v_exp_f32_e32 v112, v112
	v_exp_f32_e32 v113, v113
	v_mfma_f32_32x32x16_bf16 v[64:79], v[162:165], v[132:135], v[64:79]
	v_exp_f32_e32 v114, v114
	v_exp_f32_e32 v115, v115
	v_mfma_f32_32x32x16_bf16 v[200:215], v[162:165], v[180:183], v[200:215]
	v_exp_f32_e32 v116, v116
	v_exp_f32_e32 v117, v117
	v_exp_f32_e32 v118, v118
	v_exp_f32_e32 v119, v119
	v_cvt_pk_bf16_f32 v162, v112, v113
	v_cvt_pk_bf16_f32 v163, v114, v115
	v_cvt_pk_bf16_f32 v164, v116, v117
	v_cvt_pk_bf16_f32 v165, v118, v119
	s_nop 1
	v_mfma_f32_32x32x16_bf16 v[80:95], v[162:165], v[184:187], v[80:95]
	v_exp_f32_e32 v120, v120
	v_exp_f32_e32 v121, v121
	v_mfma_f32_32x32x16_bf16 v[64:79], v[162:165], v[132:135], v[64:79]
	v_exp_f32_e32 v122, v122
	v_exp_f32_e32 v123, v123
	v_mfma_f32_32x32x16_bf16 v[200:215], v[162:165], v[188:191], v[200:215]
	v_exp_f32_e32 v124, v124
	v_exp_f32_e32 v125, v125
	v_exp_f32_e32 v126, v126
	v_exp_f32_e32 v127, v127
	v_cvt_pk_bf16_f32 v162, v120, v121
	v_cvt_pk_bf16_f32 v163, v122, v123
	v_cvt_pk_bf16_f32 v164, v124, v125
	v_cvt_pk_bf16_f32 v165, v126, v127
	s_nop 1
	v_mfma_f32_32x32x16_bf16 v[80:95], v[162:165], v[192:195], v[80:95]
	v_mfma_f32_32x32x16_bf16 v[64:79], v[162:165], v[132:135], v[64:79]
	v_mfma_f32_32x32x16_bf16 v[200:215], v[162:165], v[196:199], v[200:215]
	s_waitcnt lgkmcnt(0)
	v_mfma_f32_32x32x16_bf16 v[96:111], v[48:51], v[136:139], 0
	ds_read_b64_tr_b16 v[168:169], v146 offset:40960
	ds_read_b64_tr_b16 v[170:171], v146 offset:41984
	ds_read_b64_tr_b16 v[172:173], v146 offset:41472
	ds_read_b64_tr_b16 v[174:175], v146 offset:42496
	v_mfma_f32_32x32x16_bf16 v[96:111], v[52:55], v[140:143], v[96:111]
	ds_read_b64_tr_b16 v[176:177], v146 offset:43008
	ds_read_b64_tr_b16 v[178:179], v146 offset:44032
	ds_read_b64_tr_b16 v[180:181], v146 offset:43520
	ds_read_b64_tr_b16 v[182:183], v146 offset:44544
	v_mfma_f32_32x32x16_bf16 v[112:127], v[56:59], v[136:139], 0
	ds_read_b64_tr_b16 v[184:185], v146 offset:45056
	ds_read_b64_tr_b16 v[186:187], v146 offset:46080
	ds_read_b64_tr_b16 v[188:189], v146 offset:45568
	ds_read_b64_tr_b16 v[190:191], v146 offset:46592
	v_mfma_f32_32x32x16_bf16 v[112:127], v[60:63], v[140:143], v[112:127]
	ds_read_b64_tr_b16 v[192:193], v146 offset:47104
	ds_read_b64_tr_b16 v[194:195], v146 offset:48128
	ds_read_b64_tr_b16 v[196:197], v146 offset:47616
	ds_read_b64_tr_b16 v[198:199], v146 offset:48640
	v_exp_f32_e32 v96, v96
	v_exp_f32_e32 v97, v97
	v_exp_f32_e32 v98, v98
	v_exp_f32_e32 v99, v99
	v_exp_f32_e32 v100, v100
	v_exp_f32_e32 v101, v101
	v_exp_f32_e32 v102, v102
	v_exp_f32_e32 v103, v103
	v_cvt_pk_bf16_f32 v162, v96, v97
	v_cvt_pk_bf16_f32 v163, v98, v99
	v_cvt_pk_bf16_f32 v164, v100, v101
	v_cvt_pk_bf16_f32 v165, v102, v103
	s_waitcnt lgkmcnt(12)
	s_nop 0
	v_mfma_f32_32x32x16_bf16 v[0:15], v[162:165], v[168:171], v[0:15]
	v_exp_f32_e32 v104, v104
	v_exp_f32_e32 v105, v105
	v_mfma_f32_32x32x16_bf16 v[32:47], v[162:165], v[132:135], v[32:47]
	v_exp_f32_e32 v106, v106
	v_exp_f32_e32 v107, v107
	v_mfma_f32_32x32x16_bf16 v[16:31], v[162:165], v[172:175], v[16:31]
	v_exp_f32_e32 v108, v108
	v_exp_f32_e32 v109, v109
	v_exp_f32_e32 v110, v110
	v_exp_f32_e32 v111, v111
	v_cvt_pk_bf16_f32 v162, v104, v105
	v_cvt_pk_bf16_f32 v163, v106, v107
	v_cvt_pk_bf16_f32 v164, v108, v109
	v_cvt_pk_bf16_f32 v165, v110, v111
	s_waitcnt lgkmcnt(8)
	s_nop 0
	v_mfma_f32_32x32x16_bf16 v[0:15], v[162:165], v[176:179], v[0:15]
	v_exp_f32_e32 v112, v112
	v_exp_f32_e32 v113, v113
	v_mfma_f32_32x32x16_bf16 v[32:47], v[162:165], v[132:135], v[32:47]
	v_exp_f32_e32 v114, v114
	v_exp_f32_e32 v115, v115
	v_mfma_f32_32x32x16_bf16 v[16:31], v[162:165], v[180:183], v[16:31]
	v_mfma_f32_32x32x16_bf16 v[96:111], v[48:51], v[150:153], 0
	v_exp_f32_e32 v116, v116
	v_exp_f32_e32 v117, v117
	v_exp_f32_e32 v118, v118
	v_exp_f32_e32 v119, v119
	v_mfma_f32_32x32x16_bf16 v[96:111], v[52:55], v[154:157], v[96:111]
	v_cvt_pk_bf16_f32 v162, v112, v113
	v_cvt_pk_bf16_f32 v163, v114, v115
	v_cvt_pk_bf16_f32 v164, v116, v117
	v_cvt_pk_bf16_f32 v165, v118, v119
	s_waitcnt lgkmcnt(4)
	s_nop 0
	v_mfma_f32_32x32x16_bf16 v[0:15], v[162:165], v[184:187], v[0:15]
	v_exp_f32_e32 v120, v120
	v_exp_f32_e32 v121, v121
	v_mfma_f32_32x32x16_bf16 v[32:47], v[162:165], v[132:135], v[32:47]
	v_exp_f32_e32 v122, v122
	v_exp_f32_e32 v123, v123
	v_mfma_f32_32x32x16_bf16 v[16:31], v[162:165], v[188:191], v[16:31]
	v_exp_f32_e32 v124, v124
	v_exp_f32_e32 v125, v125
	v_exp_f32_e32 v126, v126
	v_exp_f32_e32 v127, v127
	v_cvt_pk_bf16_f32 v162, v120, v121
	v_cvt_pk_bf16_f32 v163, v122, v123
	v_cvt_pk_bf16_f32 v164, v124, v125
	v_cvt_pk_bf16_f32 v165, v126, v127
	v_mfma_f32_32x32x16_bf16 v[112:127], v[56:59], v[150:153], 0
	v_mfma_f32_32x32x16_bf16 v[112:127], v[60:63], v[154:157], v[112:127]
	s_waitcnt lgkmcnt(0)
	s_nop 0
	v_mfma_f32_32x32x16_bf16 v[0:15], v[162:165], v[192:195], v[0:15]
	v_exp_f32_e32 v96, v96
	v_exp_f32_e32 v97, v97
	v_mfma_f32_32x32x16_bf16 v[32:47], v[162:165], v[132:135], v[32:47]
	v_exp_f32_e32 v98, v98
	v_exp_f32_e32 v99, v99
	v_mfma_f32_32x32x16_bf16 v[16:31], v[162:165], v[196:199], v[16:31]
	v_exp_f32_e32 v100, v100
	v_exp_f32_e32 v101, v101
	v_exp_f32_e32 v102, v102
	v_exp_f32_e32 v103, v103
	v_cvt_pk_bf16_f32 v162, v96, v97
	v_cvt_pk_bf16_f32 v163, v98, v99
	v_cvt_pk_bf16_f32 v164, v100, v101
	v_cvt_pk_bf16_f32 v165, v102, v103
	s_nop 1
	v_mfma_f32_32x32x16_bf16 v[80:95], v[162:165], v[168:171], v[80:95]
	v_exp_f32_e32 v104, v104
	v_exp_f32_e32 v105, v105
	v_mfma_f32_32x32x16_bf16 v[64:79], v[162:165], v[132:135], v[64:79]
	v_exp_f32_e32 v106, v106
	v_exp_f32_e32 v107, v107
	v_mfma_f32_32x32x16_bf16 v[200:215], v[162:165], v[172:175], v[200:215]
	v_exp_f32_e32 v108, v108
	v_exp_f32_e32 v109, v109
	v_exp_f32_e32 v110, v110
	v_exp_f32_e32 v111, v111
	v_cvt_pk_bf16_f32 v162, v104, v105
	v_cvt_pk_bf16_f32 v163, v106, v107
	v_cvt_pk_bf16_f32 v164, v108, v109
	v_cvt_pk_bf16_f32 v165, v110, v111
	s_nop 1
	v_mfma_f32_32x32x16_bf16 v[80:95], v[162:165], v[176:179], v[80:95]
	v_exp_f32_e32 v112, v112
	v_exp_f32_e32 v113, v113
	v_mfma_f32_32x32x16_bf16 v[64:79], v[162:165], v[132:135], v[64:79]
	v_exp_f32_e32 v114, v114
	v_exp_f32_e32 v115, v115
	v_mfma_f32_32x32x16_bf16 v[200:215], v[162:165], v[180:183], v[200:215]
	v_exp_f32_e32 v116, v116
	v_exp_f32_e32 v117, v117
	v_exp_f32_e32 v118, v118
	v_exp_f32_e32 v119, v119
	v_cvt_pk_bf16_f32 v162, v112, v113
	v_cvt_pk_bf16_f32 v163, v114, v115
	v_cvt_pk_bf16_f32 v164, v116, v117
	v_cvt_pk_bf16_f32 v165, v118, v119
	s_nop 1
	v_mfma_f32_32x32x16_bf16 v[80:95], v[162:165], v[184:187], v[80:95]
	v_exp_f32_e32 v120, v120
	v_exp_f32_e32 v121, v121
	v_mfma_f32_32x32x16_bf16 v[64:79], v[162:165], v[132:135], v[64:79]
	v_exp_f32_e32 v122, v122
	v_exp_f32_e32 v123, v123
	v_mfma_f32_32x32x16_bf16 v[200:215], v[162:165], v[188:191], v[200:215]
	v_exp_f32_e32 v124, v124
	v_exp_f32_e32 v125, v125
	v_exp_f32_e32 v126, v126
	v_exp_f32_e32 v127, v127
	v_cvt_pk_bf16_f32 v162, v120, v121
	v_cvt_pk_bf16_f32 v163, v122, v123
	v_cvt_pk_bf16_f32 v164, v124, v125
	v_cvt_pk_bf16_f32 v165, v126, v127
	s_cmp_eq_u32 s33, 21
	s_cbranch_scc1 .Lat_w0F5
	s_waitcnt vmcnt(4)
	s_branch .Lat_wdF5

; __device__ __forceinline__ int crow(int r, int hi) { return (r & 3) + 8 * (r >> 2) + 4 * hi; }
; #define AT_LOAD(K0, K1, V0, V1, T) do { const size_t e_ = (size_t)(128 * (T) + sr) * 64 + sc; \
;         K0 = *(const bf16x8*)(kcp + e_); V0 = *(const bf16x8*)(vcp + e_); K1 = *(const bf16x8*)(kcp + e_ + 64 * 64); V1 = *(const bf16x8*)(vcp + e_ + 64 * 64); } while (0)
; #define AT_STORE(K0, K1, V0, V1, BUF) do { *(LAS bf16x8*)(lds + AT_K + (BUF) * AT_KB + kst0) = K0; *(LAS bf16x8*)(lds + AT_K + (BUF) * AT_KB + kst1) = K1; \
;         *(LAS bf16x8*)(lds + AT_V + (BUF) * AT_VB + vst0) = V0; *(LAS bf16x8*)(lds + AT_V + (BUF) * AT_VB + vst1) = V1; } while (0)
; template <int VAR>
; __device__ __forceinline__ void attn_unit(const Args& a, int l, int b, int h, int qrow0  , bool ctxu, const bf16* Z, bf16* Y, LAS unsigned char* lds) {
;     ...
;     for (int t = 0; t < NT; t += 2) {
;         __syncthreads();
;         if (t + 2 < NT) AT_LOAD(ka0, ka1, va0, va1, t + 2);
;         attn_tile(Kb0, vb0, q0, q1, negm, m, o0, o1, lacc, t == 0, wsf, r32, hi);
;         AT_STORE(kb0, kb1, vb0_, vb1_, 1);
;         __syncthreads();
;         if (t + 3 < NT) AT_LOAD(kb0, kb1, vb0_, vb1_, t + 3);
;         attn_tile(Kb0 + AT_KB, vb0 + AT_VB, q0, q1, negm, m, o0, o1, lacc, false, wsf, r32, hi);
;         if (t + 2 < NT) AT_STORE(ka0, ka1, va0, va1, 0);
;     }
;     ...
;     if (comp == 1) {
; #pragma unroll
;         for (int r = 0; r < 16; ++r) { const int qr = crow(r, hi); const float il = lam * __builtin_amdgcn_rcpf(lacc[r]); stg[qr * 64 + r32] = o0[r] * il; stg[qr * 64 + 32 + r32] = o1[r] * il; }
;     }
;     __syncthreads();
;     if (comp == 0) {
; #pragma unroll
;         for (int r = 0; r < 16; ++r) { const int qr = crow(r, hi); const float il = __builtin_amdgcn_rcpf(lacc[r]); o0[r] = o0[r] * il - stg[qr * 64 + r32]; o1[r] = o1[r] * il - stg[qr * 64 + 32 + r32]; }
;         asm volatile("s_waitcnt lgkmcnt(0)" ::: "memory");
; #pragma unroll
;         for (int r = 0; r < 16; ++r) { const int qr = crow(r, hi); stg[qr * 64 + r32] = o0[r]; stg[qr * 64 + 32 + r32] = o1[r]; }
;         asm volatile("s_waitcnt lgkmcnt(0)" ::: "memory");
;         const int ch = lane & 7;
;         float gsub[8];
; #pragma unroll
;         for (int i = 0; i < 8; ++i) gsub[i] = a.subln_g[l * 64 + ch * 8 + i] * omli;
.Lat_ndF5:
	ds_read_b128 v[48:51], v144 offset:0
	ds_read_b128 v[52:55], v145 offset:0
	ds_read_b128 v[56:59], v144 offset:4096
	ds_read_b128 v[60:63], v145 offset:4096
	s_nop 1
	v_mfma_f32_32x32x16_bf16 v[80:95], v[162:165], v[192:195], v[80:95]
	v_mfma_f32_32x32x16_bf16 v[64:79], v[162:165], v[132:135], v[64:79]
	v_mfma_f32_32x32x16_bf16 v[200:215], v[162:165], v[196:199], v[200:215]
	s_add_u32 s33, s33, 1
	s_cmp_lt_u32 s33, 22
	s_cbranch_scc1 .Lat_floop
	s_nop 7
	s_nop 7
	v_add_f32_e32 v132, v32, v64
	v_min_f32_e32 v134, v32, v64
	v_add_f32_e32 v132, v132, v33
	v_add_f32_e32 v132, v132, v65
	v_min3_f32 v134, v134, v33, v65
	v_add_f32_e32 v132, v132, v34
	v_add_f32_e32 v132, v132, v66
	v_min3_f32 v134, v134, v34, v66
	v_add_f32_e32 v132, v132, v35
	v_add_f32_e32 v132, v132, v67
	v_min3_f32 v134, v134, v35, v67
	v_add_f32_e32 v132, v132, v36
	v_add_f32_e32 v132, v132, v68
	v_min3_f32 v134, v134, v36, v68
	v_add_f32_e32 v132, v132, v37
	v_add_f32_e32 v132, v132, v69
	v_min3_f32 v134, v134, v37, v69
	v_add_f32_e32 v132, v132, v38
	v_add_f32_e32 v132, v132, v70
	v_min3_f32 v134, v134, v38, v70
	v_add_f32_e32 v132, v132, v39
	v_add_f32_e32 v132, v132, v71
	v_min3_f32 v134, v134, v39, v71
	v_add_f32_e32 v132, v132, v40
	v_add_f32_e32 v132, v132, v72
	v_min3_f32 v134, v134, v40, v72
	v_add_f32_e32 v132, v132, v41
	v_add_f32_e32 v132, v132, v73
	v_min3_f32 v134, v134, v41, v73
	v_add_f32_e32 v132, v132, v42
	v_add_f32_e32 v132, v132, v74
	v_min3_f32 v134, v134, v42, v74
	v_add_f32_e32 v132, v132, v43
	v_add_f32_e32 v132, v132, v75
	v_min3_f32 v134, v134, v43, v75
	v_add_f32_e32 v132, v132, v44
	v_add_f32_e32 v132, v132, v76
	v_min3_f32 v134, v134, v44, v76
	v_add_f32_e32 v132, v132, v45
	v_add_f32_e32 v132, v132, v77
	v_min3_f32 v134, v134, v45, v77
	v_add_f32_e32 v132, v132, v46
	v_add_f32_e32 v132, v132, v78
	v_min3_f32 v134, v134, v46, v78
	v_add_f32_e32 v132, v132, v47
	v_add_f32_e32 v132, v132, v79
	v_min3_f32 v134, v134, v47, v79
	v_mov_b32_e32 v133, 0
	v_add_f32_e64 v132, v132, |v0|
	v_add_f32_e64 v133, v133, |v1|
	v_add_f32_e64 v132, v132, |v2|
	v_add_f32_e64 v133, v133, |v3|
	v_add_f32_e64 v132, v132, |v4|
	v_add_f32_e64 v133, v133, |v5|
	v_add_f32_e64 v132, v132, |v6|
	v_add_f32_e64 v133, v133, |v7|
	v_add_f32_e64 v132, v132, |v8|
	v_add_f32_e64 v133, v133, |v9|
	v_add_f32_e64 v132, v132, |v10|
	v_add_f32_e64 v133, v133, |v11|
	v_add_f32_e64 v132, v132, |v12|
	v_add_f32_e64 v133, v133, |v13|
	v_add_f32_e64 v132, v132, |v14|
	v_add_f32_e64 v133, v133, |v15|
	v_add_f32_e64 v132, v132, |v16|
	v_add_f32_e64 v133, v133, |v17|
	v_add_f32_e64 v132, v132, |v18|
	v_add_f32_e64 v133, v133, |v19|
	v_add_f32_e64 v132, v132, |v20|
	v_add_f32_e64 v133, v133, |v21|
	v_add_f32_e64 v132, v132, |v22|
	v_add_f32_e64 v133, v133, |v23|
	v_add_f32_e64 v132, v132, |v24|
	v_add_f32_e64 v133, v133, |v25|
	v_add_f32_e64 v132, v132, |v26|
	v_add_f32_e64 v133, v133, |v27|
	v_add_f32_e64 v132, v132, |v28|
	v_add_f32_e64 v133, v133, |v29|
	v_add_f32_e64 v132, v132, |v30|
	v_add_f32_e64 v133, v133, |v31|
	v_add_f32_e64 v132, v132, |v80|
	v_add_f32_e64 v133, v133, |v81|
	v_add_f32_e64 v132, v132, |v82|
	v_add_f32_e64 v133, v133, |v83|
	v_add_f32_e64 v132, v132, |v84|
	v_add_f32_e64 v133, v133, |v85|
	v_add_f32_e64 v132, v132, |v86|
	v_add_f32_e64 v133, v133, |v87|
	v_add_f32_e64 v132, v132, |v88|
	v_add_f32_e64 v133, v133, |v89|
	v_add_f32_e64 v132, v132, |v90|
	v_add_f32_e64 v133, v133, |v91|
	v_add_f32_e64 v132, v132, |v92|
	v_add_f32_e64 v133, v133, |v93|
	v_add_f32_e64 v132, v132, |v94|
	v_add_f32_e64 v133, v133, |v95|
	v_add_f32_e64 v132, v132, |v200|
	v_add_f32_e64 v133, v133, |v201|
	v_add_f32_e64 v132, v132, |v202|
	v_add_f32_e64 v133, v133, |v203|
	v_add_f32_e64 v132, v132, |v204|
	v_add_f32_e64 v133, v133, |v205|
	v_add_f32_e64 v132, v132, |v206|
	v_add_f32_e64 v133, v133, |v207|
	v_add_f32_e64 v132, v132, |v208|
	v_add_f32_e64 v133, v133, |v209|
	v_add_f32_e64 v132, v132, |v210|
	v_add_f32_e64 v133, v133, |v211|
	v_add_f32_e64 v132, v132, |v212|
	v_add_f32_e64 v133, v133, |v213|
	v_add_f32_e64 v132, v132, |v214|
	v_add_f32_e64 v133, v133, |v215|
	v_add_f32_e32 v132, v132, v133
	v_mov_b32_e32 v133, 0x76800000
	v_cmp_nlt_f32_e32 vcc, v132, v133
	v_mov_b32_e32 v132, v134
	v_mov_b32_e32 v133, 0x0d800000
	s_mov_b64 s[94:95], vcc
	v_cmp_nge_f32_e32 vcc, v132, v133
	s_or_b64 vcc, vcc, s[94:95]
	s_cmp_lg_u64 vcc, 0
	s_cselect_b32 s50, 1, 0
	v_mov_b32_e32 v134, 0x19880
	v_mov_b32_e32 v133, s50
	ds_or_b32 v134, v133
	s_waitcnt lgkmcnt(0)
	s_barrier
	ds_read_b32 v133, v134
	s_waitcnt lgkmcnt(0)
	v_readfirstlane_b32 s50, v133
	s_cmp_lg_u32 s50, 0
	s_cbranch_scc1 .Lat_safe_entry
	s_nop 7
	v_mov_b32_e32 v104, v64
	v_mov_b32_e32 v105, v65
	v_mov_b32_e32 v106, v66
	v_mov_b32_e32 v107, v67
	v_mov_b32_e32 v108, v68
	v_mov_b32_e32 v109, v69
	v_mov_b32_e32 v110, v70
	v_mov_b32_e32 v111, v71
	v_mov_b32_e32 v112, v72
	v_mov_b32_e32 v113, v73
	v_mov_b32_e32 v114, v74
	v_mov_b32_e32 v115, v75
	v_mov_b32_e32 v116, v76
	v_mov_b32_e32 v117, v77
	v_mov_b32_e32 v118, v78
	v_mov_b32_e32 v119, v79
	s_mov_b32 s94, 2
	s_mov_b32 s93, 0
	s_waitcnt vmcnt(0)
	v_or_b32_e32 v132, s58, v228
	v_mov_b32_e32 v133, 0
	v_lshl_add_u64 v[132:133], v[132:133], 2, s[78:79]
	global_load_dwordx4 v[100:103], v[132:133], off offset:16
	global_load_dwordx4 v[96:99], v[132:133], off
	s_setprio 0
	s_branch .LBB0_459

; __device__ __forceinline__ int crow(int r, int hi) { return (r & 3) + 8 * (r >> 2) + 4 * hi; }
; template <int VAR>
; __device__ __forceinline__ void attn_unit(const Args& a, int l, int b, int h, int qrow0  , bool ctxu, const bf16* Z, bf16* Y, LAS unsigned char* lds) {
;     ...
;     if (comp == 1) {
; #pragma unroll
;         for (int r = 0; r < 16; ++r) { const int qr = crow(r, hi); const float il = lam * __builtin_amdgcn_rcpf(lacc[r]); stg[qr * 64 + r32] = o0[r] * il; stg[qr * 64 + 32 + r32] = o1[r] * il; }
;     }
;     __syncthreads();
;     if (comp == 0) {
; #pragma unroll
;         for (int r = 0; r < 16; ++r) { const int qr = crow(r, hi); const float il = __builtin_amdgcn_rcpf(lacc[r]); o0[r] = o0[r] * il - stg[qr * 64 + r32]; o1[r] = o1[r] * il - stg[qr * 64 + 32 + r32]; }
;         asm volatile("s_waitcnt lgkmcnt(0)" ::: "memory");
; #pragma unroll
;         for (int r = 0; r < 16; ++r) { const int qr = crow(r, hi); stg[qr * 64 + r32] = o0[r]; stg[qr * 64 + 32 + r32] = o1[r]; }
.Lat_passB:
	s_mov_b32 s93, 1
	s_barrier
	v_mov_b32_e32 v0, v80
	v_mov_b32_e32 v16, v200
	v_mov_b32_e32 v1, v81
	v_mov_b32_e32 v17, v201
	v_mov_b32_e32 v2, v82
	v_mov_b32_e32 v18, v202
	v_mov_b32_e32 v3, v83
	v_mov_b32_e32 v19, v203
	v_mov_b32_e32 v4, v84
	v_mov_b32_e32 v20, v204
	v_mov_b32_e32 v5, v85
	v_mov_b32_e32 v21, v205
	v_mov_b32_e32 v6, v86
	v_mov_b32_e32 v22, v206
	v_mov_b32_e32 v7, v87
	v_mov_b32_e32 v23, v207
	v_mov_b32_e32 v8, v88
	v_mov_b32_e32 v24, v208
	v_mov_b32_e32 v9, v89
	v_mov_b32_e32 v25, v209
	v_mov_b32_e32 v10, v90
	v_mov_b32_e32 v26, v210
	v_mov_b32_e32 v11, v91
	v_mov_b32_e32 v27, v211
	v_mov_b32_e32 v12, v92
	v_mov_b32_e32 v28, v212
	v_mov_b32_e32 v13, v93
	v_mov_b32_e32 v29, v213
	v_mov_b32_e32 v14, v94
	v_mov_b32_e32 v30, v214
	v_mov_b32_e32 v15, v95
	v_mov_b32_e32 v31, v215
	s_cmp_eq_u32 s94, 2
	s_cbranch_scc0 .Lat_pbrows
	v_mov_b32_e32 v32, v104
	v_mov_b32_e32 v33, v105
	v_mov_b32_e32 v34, v106
	v_mov_b32_e32 v35, v107
	v_mov_b32_e32 v36, v108
	v_mov_b32_e32 v37, v109
	v_mov_b32_e32 v38, v110
	v_mov_b32_e32 v39, v111
	v_mov_b32_e32 v40, v112
	v_mov_b32_e32 v41, v113
	v_mov_b32_e32 v42, v114
	v_mov_b32_e32 v43, v115
	v_mov_b32_e32 v44, v116
	v_mov_b32_e32 v45, v117
	v_mov_b32_e32 v46, v118
	v_mov_b32_e32 v47, v119
	s_branch .Lat_pbjoin
.Lat_pbrows:
	s_waitcnt lgkmcnt(0)
	ds_write_b32 v148, v130
	s_waitcnt lgkmcnt(0)
	ds_read_b128 v[32:35], v147 offset:0
	ds_read_b128 v[36:39], v147 offset:32
	ds_read_b128 v[40:43], v147 offset:64
	ds_read_b128 v[44:47], v147 offset:96
	s_waitcnt lgkmcnt(0)
.Lat_pbjoin:
	v_mbcnt_lo_u32_b32 v227, -1, 0
	v_mbcnt_hi_u32_b32 v227, -1, v227
	s_or_b32 s60, s60, 0x1000
	s_bfe_u32 s9, s29, 0x20006
	s_ashr_i32 s8, s29, 8
	s_branch .LBB0_459

; __device__ __forceinline__ int crow(int r, int hi) { return (r & 3) + 8 * (r >> 2) + 4 * hi; }
; #define AT_LOAD(K0, K1, V0, V1, T) do { const size_t e_ = (size_t)(128 * (T) + sr) * 64 + sc; \
;         K0 = *(const bf16x8*)(kcp + e_); V0 = *(const bf16x8*)(vcp + e_); K1 = *(const bf16x8*)(kcp + e_ + 64 * 64); V1 = *(const bf16x8*)(vcp + e_ + 64 * 64); } while (0)
; #define AT_STORE(K0, K1, V0, V1, BUF) do { *(LAS bf16x8*)(lds + AT_K + (BUF) * AT_KB + kst0) = K0; *(LAS bf16x8*)(lds + AT_K + (BUF) * AT_KB + kst1) = K1; \
;         *(LAS bf16x8*)(lds + AT_V + (BUF) * AT_VB + vst0) = V0; *(LAS bf16x8*)(lds + AT_V + (BUF) * AT_VB + vst1) = V1; } while (0)
; template <int VAR>
; __device__ __forceinline__ void attn_unit(const Args& a, int l, int b, int h, int qrow0  , bool ctxu, const bf16* Z, bf16* Y, LAS unsigned char* lds) {
;     ...
;     for (int t = 0; t < NT; t += 2) {
;         __syncthreads();
;         if (t + 2 < NT) AT_LOAD(ka0, ka1, va0, va1, t + 2);
;         attn_tile(Kb0, vb0, q0, q1, negm, m, o0, o1, lacc, t == 0, wsf, r32, hi);
;         AT_STORE(kb0, kb1, vb0_, vb1_, 1);
;         __syncthreads();
;         if (t + 3 < NT) AT_LOAD(kb0, kb1, vb0_, vb1_, t + 3);
;         attn_tile(Kb0 + AT_KB, vb0 + AT_VB, q0, q1, negm, m, o0, o1, lacc, false, wsf, r32, hi);
;         if (t + 2 < NT) AT_STORE(ka0, ka1, va0, va1, 0);
;     }
;     ...
;     if (comp == 1) {
; #pragma unroll
;         for (int r = 0; r < 16; ++r) { const int qr = crow(r, hi); const float il = lam * __builtin_amdgcn_rcpf(lacc[r]); stg[qr * 64 + r32] = o0[r] * il; stg[qr * 64 + 32 + r32] = o1[r] * il; }
;     }
;     __syncthreads();
;     if (comp == 0) {
; #pragma unroll
;         for (int r = 0; r < 16; ++r) { const int qr = crow(r, hi); const float il = __builtin_amdgcn_rcpf(lacc[r]); o0[r] = o0[r] * il - stg[qr * 64 + r32]; o1[r] = o1[r] * il - stg[qr * 64 + 32 + r32]; }
;         asm volatile("s_waitcnt lgkmcnt(0)" ::: "memory");
; #pragma unroll
;         for (int r = 0; r < 16; ++r) { const int qr = crow(r, hi); stg[qr * 64 + r32] = o0[r]; stg[qr * 64 + 32 + r32] = o1[r]; }
;         asm volatile("s_waitcnt lgkmcnt(0)" ::: "memory");
;         const int ch = lane & 7;
;         float gsub[8];
; #pragma unroll
;         for (int i = 0; i < 8; ++i) gsub[i] = a.subln_g[l * 64 + ch * 8 + i] * omli;
.Lat_ndg5:
	ds_read_b128 v[48:51], v144 offset:0
	ds_read_b128 v[52:55], v145 offset:0
	ds_read_b128 v[56:59], v144 offset:4096
	ds_read_b128 v[60:63], v145 offset:4096
	v_mfma_f32_32x32x16_bf16 v[80:95], v[162:165], v[192:195], v[80:95]
	v_mfma_f32_32x32x16_bf16 v[200:215], v[162:165], v[196:199], v[200:215]
	s_add_u32 s33, s33, 1
	s_cmp_lt_u32 s33, 22
	s_cbranch_scc1 .Lat_loop
	v_add_f32_e32 v132, v128, v129
	v_mov_b32_e32 v133, v132
	s_nop 1
	v_permlane32_swap_b32_e32 v132, v133
	v_add_f32_e32 v135, v132, v133
	v_add_f32_e32 v132, v130, v131
	v_mov_b32_e32 v133, v132
	s_nop 1
	v_permlane32_swap_b32_e32 v132, v133
	v_add_f32_e32 v130, v132, v133
	s_nop 7
	s_waitcnt lgkmcnt(0)
	ds_write_b32 v148, v135
	s_waitcnt lgkmcnt(0)
	ds_read_b128 v[32:35], v147 offset:0
	ds_read_b128 v[36:39], v147 offset:32
	ds_read_b128 v[40:43], v147 offset:64
	ds_read_b128 v[44:47], v147 offset:96
	s_waitcnt lgkmcnt(0)
	s_mov_b32 s94, 0
	s_mov_b32 s93, 0
	s_waitcnt vmcnt(0)
	v_or_b32_e32 v132, s58, v228
	v_mov_b32_e32 v133, 0
	v_lshl_add_u64 v[132:133], v[132:133], 2, s[78:79]
	global_load_dwordx4 v[100:103], v[132:133], off offset:16
	global_load_dwordx4 v[96:99], v[132:133], off
	s_setprio 0
	s_branch .LBB0_459
